# sample pool: wave 0 no longer waits on the next-claim atomic before its item (result read at publish time); lever 2 de-serialisation; on top of v67
# baseline (speedup 1.0000x reference)
.LBB0_1072:
	v_mov_b32_e32 v49, 0
	s_mov_b64 s[4:5], exec
	v_readlane_b32 s44, v252, 45
	v_readlane_b32 s45, v252, 46
	s_and_b64 s[44:45], s[4:5], s[44:45]
	s_mov_b64 exec, s[44:45]
	s_cbranch_execz .LBB0_1076
	s_mov_b64 s[60:61], exec
	v_mbcnt_lo_u32_b32 v2, s60, 0
	v_mbcnt_hi_u32_b32 v2, s61, v2
	v_cmp_eq_u32_e32 vcc, 0, v2
	s_and_saveexec_b64 s[44:45], vcc
	s_cbranch_execz .LBB0_1075
	s_bcnt1_i32_b64 s60, s[60:61]
	v_mov_b32_e32 v3, s60
	global_atomic_add v174, v47, v3, s[46:47] sc0
.LBB0_1075:
	s_or_b64 exec, exec, s[44:45]
.LBB0_1076:
	s_or_b64 exec, exec, s[4:5]
	s_lshl_b32 s4, s52, 3
	s_add_i32 s4, s4, s67
	s_and_b32 s5, s4, 31
	s_lshl_b32 s44, s5, 6
	v_add_u32_e32 v22, s44, v18
	s_lshr_b32 s52, s4, 5
	v_ashrrev_i32_e32 v23, 31, v22
	s_mul_i32 s4, s5, 0x3c0
	v_lshlrev_b64 v[2:3], 5, v[22:23]
	v_lshlrev_b64 v[4:5], 7, v[22:23]
	v_add_u32_e32 v22, s4, v22
	v_readlane_b32 s68, v252, 24
	v_ashrrev_i32_e32 v23, 31, v22
	v_readlane_b32 s69, v252, 25
	v_readlane_b32 s70, v252, 26
	v_readlane_b32 s71, v252, 27
	v_readlane_b32 s80, v252, 36
	v_readlane_b32 s81, v252, 37
	v_lshlrev_b64 v[22:23], 2, v[22:23]
	v_readlane_b32 s82, v252, 38
	v_readlane_b32 s83, v252, 39
	s_mov_b64 s[68:69], s[80:81]
	v_lshl_add_u64 v[2:3], s[54:55], 0, v[2:3]
	v_lshl_add_u64 v[14:15], s[56:57], 0, v[4:5]
	s_mov_b64 s[70:71], s[82:83]
	v_lshl_add_u64 v[24:25], s[68:69], 0, v[22:23]
	global_load_dwordx2 v[44:45], v[2:3], off
	global_load_dwordx4 v[98:101], v[14:15], off
	global_load_dwordx4 v[40:43], v[14:15], off offset:16
	global_load_dwordx4 v[36:39], v[14:15], off offset:32
	global_load_dwordx4 v[32:35], v[14:15], off offset:48
	s_nop 0
	global_load_dwordx4 v[2:5], v[14:15], off offset:64
	global_load_dwordx4 v[6:9], v[14:15], off offset:80
	global_load_dwordx4 v[10:13], v[14:15], off offset:96
	s_nop 0
	global_load_dwordx4 v[14:17], v[14:15], off offset:112
	v_lshl_add_u64 v[22:23], s[70:71], 0, v[22:23]
	global_load_dword v51, v[24:25], off
	global_load_dword v53, v[24:25], off offset:256
	global_load_dword v55, v[24:25], off offset:512
	global_load_dword v57, v[24:25], off offset:768
	global_load_dword v59, v[24:25], off offset:1024
	global_load_dword v61, v[24:25], off offset:1280
	global_load_dword v63, v[24:25], off offset:1536
	global_load_dword v65, v[24:25], off offset:1792
	global_load_dword v67, v[22:23], off
	global_load_dword v69, v[22:23], off offset:256
	global_load_dword v71, v[22:23], off offset:512
	global_load_dword v73, v[22:23], off offset:768
	global_load_dword v75, v[22:23], off offset:1024
	global_load_dword v77, v[22:23], off offset:1280
	global_load_dword v78, v[22:23], off offset:1536
	global_load_dword v79, v[22:23], off offset:1792
	global_load_dword v80, v[24:25], off offset:2048
	global_load_dword v81, v[24:25], off offset:2304
	global_load_dword v82, v[24:25], off offset:2560
	global_load_dword v83, v[24:25], off offset:2816
	global_load_dword v84, v[24:25], off offset:3072
	global_load_dword v85, v[24:25], off offset:3328
	global_load_dword v86, v[24:25], off offset:3584
	global_load_dword v87, v[24:25], off offset:3840
	global_load_dword v88, v[22:23], off offset:2048
	global_load_dword v89, v[22:23], off offset:2304
	global_load_dword v90, v[22:23], off offset:2560
	global_load_dword v91, v[22:23], off offset:2816
	global_load_dword v92, v[22:23], off offset:3072
	global_load_dword v93, v[22:23], off offset:3328
	global_load_dword v94, v[22:23], off offset:3584
	global_load_dword v95, v[22:23], off offset:3840
	s_lshl_b32 s4, s52, 11
	s_or_b32 s4, s44, s4
	v_add_u32_e32 v22, s4, v18
	v_ashrrev_i32_e32 v23, 31, v22
	v_readlane_b32 s76, v252, 32
	v_readlane_b32 s77, v252, 33
	v_readlane_b32 s78, v252, 34
	v_readlane_b32 s79, v252, 35
	v_lshlrev_b64 v[24:25], 2, v[22:23]
	v_lshl_add_u64 v[22:23], s[48:49], 0, v[24:25]
	v_readlane_b32 s76, v252, 48
	global_load_dword v23, v[22:23], off
	v_lshl_or_b32 v22, v1, 2, s44
	v_readlane_b32 s77, v252, 49
	v_lshl_add_u64 v[24:25], s[50:51], 0, v[24:25]
	s_nop 3
	global_load_dword v96, v22, s[76:77]
	s_nop 0
	global_load_dword v22, v[24:25], off
	s_lshl_b64 s[44:45], s[52:53], 12
	s_lshl_b32 s5, s5, 5
	s_or_b32 s44, s44, s5
	s_add_u32 s5, s3, s44
	s_addc_u32 s52, s33, s45
	s_mov_b32 s60, s5
	s_mov_b32 s61, s52
	global_load_dwordx4 v[162:165], v47, s[60:61] offset:-16
	global_load_dwordx4 v[166:169], v47, s[60:61] offset:0
	global_load_ushort v170, v106, s[60:61] offset:-16
	global_load_dwordx4 v[130:133], v47, s[60:61] offset:1008
	global_load_dwordx4 v[134:137], v47, s[60:61] offset:1024
	global_load_ushort v171, v106, s[60:61] offset:1008
	global_load_dwordx4 v[138:141], v47, s[60:61] offset:2032
	global_load_dwordx4 v[142:145], v47, s[60:61] offset:2048
	global_load_ushort v172, v106, s[60:61] offset:2032
	global_load_dwordx4 v[150:153], v47, s[60:61] offset:3056
	global_load_dwordx4 v[154:157], v47, s[60:61] offset:3072
	global_load_ushort v173, v106, s[60:61] offset:3056
	v_readlane_b32 s72, v252, 28
	v_readlane_b32 s73, v252, 29
	v_readlane_b32 s74, v252, 30
	v_readlane_b32 s75, v252, 31
	v_readlane_b32 s78, v252, 50
	v_readlane_b32 s79, v252, 51
	v_readlane_b32 s80, v252, 52
	v_readlane_b32 s81, v252, 53
	v_readlane_b32 s82, v252, 54
	v_readlane_b32 s83, v252, 55
	s_waitcnt vmcnt(55)
	v_pk_add_f32 v[26:27], v[44:45], 0 neg_lo:[1,1] neg_hi:[1,1]
	v_mov_b32_e32 v24, v44
	v_mov_b32_e32 v25, v44
	v_mov_b32_e32 v26, v45
	s_waitcnt vmcnt(51)
	v_mov_b32_e32 v29, v35
	v_mov_b32_e32 v31, v33
	v_mov_b32_e32 v33, v39
	v_mov_b32_e32 v35, v37
	s_waitcnt vmcnt(47)
	v_mov_b32_e32 v28, v17
	v_mov_b32_e32 v17, v34
	v_mov_b32_e32 v30, v15
	v_mov_b32_e32 v15, v32
	v_mov_b32_e32 v32, v13
	v_mov_b32_e32 v13, v38
	v_mov_b32_e32 v34, v11
	v_mov_b32_e32 v11, v36
	v_mov_b32_e32 v36, v9
	v_mov_b32_e32 v37, v43
	v_mov_b32_e32 v9, v42
	v_mov_b32_e32 v38, v7
	v_mov_b32_e32 v39, v41
	v_mov_b32_e32 v7, v40
	v_mov_b32_e32 v40, v5
	v_mov_b32_e32 v41, v101
	v_mov_b32_e32 v5, v100
	v_mov_b32_e32 v42, v3
	v_mov_b32_e32 v43, v99
	v_mov_b32_e32 v3, v98
	v_lshl_add_u64 v[44:45], v[20:21], 0, s[44:45]
	s_mov_b64 s[44:45], 0
	s_waitcnt vmcnt(0)
	v_lshlrev_b32_e32 v46, 16, v162
	v_and_b32_e32 v48, 0xffff0000, v162
	v_lshlrev_b32_e32 v50, 16, v163
	v_and_b32_e32 v52, 0xffff0000, v163
	v_pk_fma_f32 v[98:99], v[2:3], v[46:47], 0 op_sel_hi:[1,0,0]
	v_lshlrev_b32_e32 v54, 16, v164
	v_pk_fma_f32 v[98:99], v[42:43], v[48:49], v[98:99] op_sel_hi:[1,0,1]
	v_and_b32_e32 v56, 0xffff0000, v164
	v_pk_fma_f32 v[98:99], v[4:5], v[50:51], v[98:99] op_sel_hi:[1,0,1]
	v_lshlrev_b32_e32 v58, 16, v165
	v_pk_fma_f32 v[98:99], v[40:41], v[52:53], v[98:99] op_sel_hi:[1,0,1]
	v_and_b32_e32 v60, 0xffff0000, v165
	v_pk_fma_f32 v[98:99], v[6:7], v[54:55], v[98:99] op_sel_hi:[1,0,1]
	v_lshlrev_b32_e32 v62, 16, v166
	v_pk_fma_f32 v[98:99], v[38:39], v[56:57], v[98:99] op_sel_hi:[1,0,1]
	v_and_b32_e32 v64, 0xffff0000, v166
	v_pk_fma_f32 v[98:99], v[8:9], v[58:59], v[98:99] op_sel_hi:[1,0,1]
	v_lshlrev_b32_e32 v66, 16, v167
	v_pk_fma_f32 v[98:99], v[36:37], v[60:61], v[98:99] op_sel_hi:[1,0,1]
	v_and_b32_e32 v68, 0xffff0000, v167
	v_pk_fma_f32 v[98:99], v[10:11], v[62:63], v[98:99] op_sel_hi:[1,0,1]
	v_lshlrev_b32_e32 v70, 16, v168
	v_pk_fma_f32 v[98:99], v[34:35], v[64:65], v[98:99] op_sel_hi:[1,0,1]
	v_and_b32_e32 v72, 0xffff0000, v168
	v_pk_fma_f32 v[98:99], v[12:13], v[66:67], v[98:99] op_sel_hi:[1,0,1]
	v_lshlrev_b32_e32 v74, 16, v169
	v_pk_fma_f32 v[98:99], v[32:33], v[68:69], v[98:99] op_sel_hi:[1,0,1]
	v_and_b32_e32 v76, 0xffff0000, v169
	v_pk_fma_f32 v[98:99], v[14:15], v[70:71], v[98:99] op_sel_hi:[1,0,1]
	s_nop 0
	v_pk_fma_f32 v[98:99], v[30:31], v[72:73], v[98:99] op_sel_hi:[1,0,1]
	s_nop 0
	v_pk_fma_f32 v[98:99], v[16:17], v[74:75], v[98:99] op_sel_hi:[1,0,1]
	s_nop 0
	v_pk_fma_f32 v[98:99], v[28:29], v[76:77], v[98:99] op_sel_hi:[1,0,1]
	s_nop 0
	v_pk_fma_f32 v[98:99], v[26:27], v[22:23], v[98:99] op_sel:[0,1,0] op_sel_hi:[1,0,1]
	s_nop 0
	v_pk_fma_f32 v[22:23], v[24:25], v[22:23], v[98:99]
	s_nop 0
	v_mul_f32_e32 v97, v67, v22
	v_mul_f32_e32 v98, v69, v22
	v_mul_f32_e32 v99, v71, v22
	v_mul_f32_e32 v100, v73, v22
	v_mul_f32_e32 v101, v75, v22
	v_mul_f32_e32 v102, v77, v22
	v_mul_f32_e32 v109, v78, v22
	v_mul_f32_e32 v111, v79, v22
	v_mul_f32_e32 v113, v88, v22
	v_mul_f32_e32 v115, v89, v22
	v_mul_f32_e32 v117, v90, v22
	v_mul_f32_e32 v119, v91, v22
	v_mul_f32_e32 v121, v92, v22
	v_mul_f32_e32 v123, v93, v22
	v_mul_f32_e32 v125, v94, v22
	v_mul_f32_e32 v127, v95, v22
	v_fma_f32 v97, v51, v23, -v97
	v_fma_f32 v98, v53, v23, -v98
	v_fma_f32 v99, v55, v23, -v99
	v_fma_f32 v100, v57, v23, -v100
	v_fma_f32 v101, v59, v23, -v101
	v_fma_f32 v102, v61, v23, -v102
	v_fma_f32 v109, v63, v23, -v109
	v_fma_f32 v111, v65, v23, -v111
	v_fma_f32 v113, v80, v23, -v113
	v_fma_f32 v115, v81, v23, -v115
	v_fma_f32 v117, v82, v23, -v117
	v_fma_f32 v119, v83, v23, -v119
	v_fma_f32 v121, v84, v23, -v121
	v_fma_f32 v123, v85, v23, -v123
	v_fma_f32 v125, v86, v23, -v125
	v_fma_f32 v127, v87, v23, -v127
	v_add_f32_dpp v97, v97, v97 row_ror:8 row_mask:0xf bank_mask:0xf bound_ctrl:1
	v_add_f32_dpp v98, v98, v98 row_ror:8 row_mask:0xf bank_mask:0xf bound_ctrl:1
	v_add_f32_dpp v99, v99, v99 row_ror:8 row_mask:0xf bank_mask:0xf bound_ctrl:1
	v_add_f32_dpp v100, v100, v100 row_ror:8 row_mask:0xf bank_mask:0xf bound_ctrl:1
	v_add_f32_dpp v101, v101, v101 row_ror:8 row_mask:0xf bank_mask:0xf bound_ctrl:1
	v_add_f32_dpp v102, v102, v102 row_ror:8 row_mask:0xf bank_mask:0xf bound_ctrl:1
	v_add_f32_dpp v109, v109, v109 row_ror:8 row_mask:0xf bank_mask:0xf bound_ctrl:1
	v_add_f32_dpp v111, v111, v111 row_ror:8 row_mask:0xf bank_mask:0xf bound_ctrl:1
	v_add_f32_dpp v113, v113, v113 row_ror:8 row_mask:0xf bank_mask:0xf bound_ctrl:1
	v_add_f32_dpp v115, v115, v115 row_ror:8 row_mask:0xf bank_mask:0xf bound_ctrl:1
	v_add_f32_dpp v117, v117, v117 row_ror:8 row_mask:0xf bank_mask:0xf bound_ctrl:1
	v_add_f32_dpp v119, v119, v119 row_ror:8 row_mask:0xf bank_mask:0xf bound_ctrl:1
	v_add_f32_dpp v121, v121, v121 row_ror:8 row_mask:0xf bank_mask:0xf bound_ctrl:1
	v_add_f32_dpp v123, v123, v123 row_ror:8 row_mask:0xf bank_mask:0xf bound_ctrl:1
	v_add_f32_dpp v125, v125, v125 row_ror:8 row_mask:0xf bank_mask:0xf bound_ctrl:1
	v_add_f32_dpp v127, v127, v127 row_ror:8 row_mask:0xf bank_mask:0xf bound_ctrl:1
	v_cndmask_b32_e64 v97, v97, v113, s[6:7]
	v_cndmask_b32_e64 v98, v98, v115, s[6:7]
	v_cndmask_b32_e64 v99, v99, v117, s[6:7]
	v_cndmask_b32_e64 v100, v100, v119, s[6:7]
	v_cndmask_b32_e64 v101, v101, v121, s[6:7]
	v_cndmask_b32_e64 v102, v102, v123, s[6:7]
	v_cndmask_b32_e64 v109, v109, v125, s[6:7]
	v_cndmask_b32_e64 v111, v111, v127, s[6:7]
	v_add_f32_dpp v97, v97, v97 row_half_mirror row_mask:0xf bank_mask:0xf bound_ctrl:1
	v_add_f32_dpp v98, v98, v98 row_half_mirror row_mask:0xf bank_mask:0xf bound_ctrl:1
	v_add_f32_dpp v99, v99, v99 row_half_mirror row_mask:0xf bank_mask:0xf bound_ctrl:1
	v_add_f32_dpp v100, v100, v100 row_half_mirror row_mask:0xf bank_mask:0xf bound_ctrl:1
	v_add_f32_dpp v101, v101, v101 row_half_mirror row_mask:0xf bank_mask:0xf bound_ctrl:1
	v_add_f32_dpp v102, v102, v102 row_half_mirror row_mask:0xf bank_mask:0xf bound_ctrl:1
	v_add_f32_dpp v109, v109, v109 row_half_mirror row_mask:0xf bank_mask:0xf bound_ctrl:1
	v_add_f32_dpp v111, v111, v111 row_half_mirror row_mask:0xf bank_mask:0xf bound_ctrl:1
	v_cndmask_b32_e64 v97, v97, v101, s[8:9]
	v_cndmask_b32_e64 v98, v98, v102, s[8:9]
	v_cndmask_b32_e64 v99, v99, v109, s[8:9]
	v_cndmask_b32_e64 v100, v100, v111, s[8:9]
	v_add_f32_dpp v97, v97, v97 quad_perm:[3,2,1,0] row_mask:0xf bank_mask:0xf bound_ctrl:1
	v_add_f32_dpp v98, v98, v98 quad_perm:[3,2,1,0] row_mask:0xf bank_mask:0xf bound_ctrl:1
	v_add_f32_dpp v99, v99, v99 quad_perm:[3,2,1,0] row_mask:0xf bank_mask:0xf bound_ctrl:1
	v_add_f32_dpp v100, v100, v100 quad_perm:[3,2,1,0] row_mask:0xf bank_mask:0xf bound_ctrl:1
	v_cndmask_b32_e64 v97, v97, v99, s[10:11]
	v_cndmask_b32_e64 v98, v98, v100, s[10:11]
	s_nop 1
	v_add_f32_dpp v97, v97, v97 quad_perm:[1,0,3,2] row_mask:0xf bank_mask:0xf bound_ctrl:1
	v_add_f32_dpp v98, v98, v98 quad_perm:[1,0,3,2] row_mask:0xf bank_mask:0xf bound_ctrl:1
	v_cndmask_b32_e64 v97, v97, v98, s[12:13]
	v_mov_b32_e32 v110, v97
	s_nop 1
	v_permlane16_swap_b32_e32 v97, v110
	v_add_f32_e32 v97, v97, v110
	v_mov_b32_e32 v110, v97
	s_nop 1
	v_permlane32_swap_b32_e32 v97, v110
	s_and_saveexec_b64 s[60:61], s[0:1]
	s_cbranch_execz .Lsmp_skip_0
	v_add_f32_e32 v97, v97, v110
	v_lshlrev_b32_e32 v46, 16, v170
	v_fma_f32 v48, v96, v46, v97
	v_mul_f32_e32 v46, 0x3d372713, v48
	v_mul_f32_e32 v46, v48, v46
	v_fma_f32 v46, v48, v46, v48
	v_mul_f32_e32 v46, 0xbfcc422a, v46
	v_mul_f32_e32 v46, 0x3fb8aa3b, v46
	v_exp_f32_e32 v46, v46
	v_lshl_add_u64 v[98:99], v[44:45], 0, s[44:45]
	v_add_f32_e32 v46, 1.0, v46
	v_rcp_f32_e32 v46, v46
	s_nop 0
	v_mul_f32_e32 v46, v48, v46
	v_cvt_pk_bf16_f32 v46, v46, v46
	global_store_short v[98:99], v46, off

.LBB0_1082:
	s_mov_b64 s[4:5], exec
	v_readlane_b32 s44, v252, 45
	v_readlane_b32 s45, v252, 46
	s_and_b64 s[44:45], s[4:5], s[44:45]
	s_mov_b64 exec, s[44:45]
	s_cbranch_execz .LBB0_1071
	s_lshl_b32 s44, s2, 2
	s_add_i32 s44, s44, 0
	s_add_i32 s44, s44, 0x20170
	v_mov_b32_e32 v2, s44
	ds_write_b32 v2, v174
	s_branch .LBB0_1071
